# attention: pre-pass K loads issued with Q loads; last PV MFMA group deferred to overlap next tile LDS latency
# baseline (speedup 1.0000x reference)
.LBB0_567:
	s_lshl_b64 s[0:1], s[20:21], 1
	s_add_u32 s0, s38, s0
	s_addc_u32 s1, s39, s1
	global_load_ushort v0, v131, s[0:1]
	s_mov_b32 s0, 0xffff
	s_waitcnt vmcnt(0)
	v_cmp_eq_u32_sdwa s[0:1], v0, s0 src0_sel:WORD_0 src1_sel:DWORD
	s_and_b64 vcc, exec, s[0:1]
	v_readfirstlane_b32 s0, v0
	s_cbranch_vccnz .LBB0_611
	s_and_b32 s30, 0xffff, s0
	s_and_b32 s4, s30, 63
	s_bfe_u32 s0, s30, 0x30006
	s_lshl_b32 s5, s4, 7
	s_lshl_b32 s2, s0, 8
	s_mov_b32 s3, s21
	v_or_b32_e32 v0, s5, v162
	v_lshl_add_u64 v[8:9], v[132:133], 0, s[2:3]
	v_lshlrev_b32_e32 v130, 11, v0
	v_or_b32_e32 v2, s5, v163
	v_lshl_add_u64 v[0:1], v[8:9], 0, v[130:131]
	v_lshlrev_b32_e32 v130, 11, v2
	v_or_b32_e32 v10, s5, v164
	v_lshl_add_u64 v[4:5], v[8:9], 0, v[130:131]
	v_lshlrev_b32_e32 v130, 11, v10
	v_lshl_add_u64 v[10:11], v[8:9], 0, v[130:131]
	v_add_lshl_u32 v130, s5, v165, 11
	v_lshl_add_u64 v[12:13], v[8:9], 0, v[130:131]
	global_load_dwordx4 v[0:3], v[0:1], off
	s_nop 0
	global_load_dwordx4 v[4:7], v[4:5], off
	s_nop 0
	global_load_dwordx4 v[8:11], v[10:11], off
	s_nop 0
	global_load_dwordx4 v[12:15], v[12:13], off
	s_lshl_b32 s80, s0, 8
	s_mov_b32 s81, s21
	v_lshl_add_u64 v[112:113], v[134:135], 0, s[80:81]
	s_lshl_b32 s2, s4, 1
	s_or_b32 s2, s2, 1
	s_lshl_b32 s2, s2, 17
	s_mov_b32 s3, s21
	v_lshl_add_u64 v[214:215], v[112:113], 0, s[2:3]
	s_lshl_b32 s2, s4, 18
	v_lshl_add_u64 v[216:217], v[112:113], 0, s[2:3]
	global_load_dwordx4 v[198:201], v[214:215], off
	global_load_dwordx4 v[206:209], v[216:217], off
	v_add_co_u32_e32 v214, vcc, 0x2000, v214
	s_nop 1
	v_addc_co_u32_e32 v215, vcc, 0, v215, vcc
	global_load_dwordx4 v[202:205], v[214:215], off
	v_add_co_u32_e32 v216, vcc, 0x2000, v216
	s_nop 1
	v_addc_co_u32_e32 v217, vcc, 0, v217, vcc
	global_load_dwordx4 v[210:213], v[216:217], off
	v_readlane_b32 s1, v240, 20
	s_lshl_b32 s1, s1, 2
	s_lshl_b32 s2, s0, 6
	s_or_b32 s1, s2, s1
	v_mov_b32_e32 v16, s1
	s_mul_i32 s1, s0, 23
	s_add_i32 s1, s1, s4
	v_sub_co_u32_e64 v18, s[8:9], s1, v185
	s_add_i32 s1, s0, 1
	v_readfirstlane_b32 s31, v18
	s_lshl_b32 s11, s0, 7
	s_waitcnt vmcnt(7)
	ds_write_b128 v176, v[0:3]
	s_waitcnt vmcnt(6)
	ds_write_b128 v177, v[4:7]
	s_waitcnt vmcnt(5)
	ds_write_b128 v178, v[8:11]
	s_waitcnt vmcnt(4)
	ds_write_b128 v179, v[12:15]
	s_waitcnt lgkmcnt(0)
	s_barrier
	global_load_dwordx4 v[0:3], v16, s[28:29] offset:16
	global_load_dwordx4 v[4:7], v16, s[28:29]
	ds_read_b128 v[8:11], v186
	ds_read_b128 v[12:15], v186 offset:4128
	s_waitcnt lgkmcnt(1)
	v_lshlrev_b32_e32 v16, 16, v8
	v_and_b32_e32 v8, 0xffff0000, v8
	v_mul_f32_e32 v8, v8, v8
	v_fmac_f32_e32 v8, v16, v16
	v_lshlrev_b32_e32 v16, 16, v9
	v_fmac_f32_e32 v8, v16, v16
	v_and_b32_e32 v9, 0xffff0000, v9
	v_fmac_f32_e32 v8, v9, v9
	v_lshlrev_b32_e32 v9, 16, v10
	v_fmac_f32_e32 v8, v9, v9
	v_and_b32_e32 v9, 0xffff0000, v10
	v_fmac_f32_e32 v8, v9, v9
	v_lshlrev_b32_e32 v9, 16, v11
	v_fmac_f32_e32 v8, v9, v9
	v_and_b32_e32 v9, 0xffff0000, v11
	v_fmac_f32_e32 v8, v9, v9
	s_waitcnt lgkmcnt(0)
	v_lshlrev_b32_e32 v9, 16, v12
	v_fmac_f32_e32 v8, v9, v9
	v_and_b32_e32 v9, 0xffff0000, v12
	v_fmac_f32_e32 v8, v9, v9
	v_lshlrev_b32_e32 v9, 16, v13
	v_fmac_f32_e32 v8, v9, v9
	v_and_b32_e32 v9, 0xffff0000, v13
	ds_read_b128 v[10:13], v186 offset:8256
	v_fmac_f32_e32 v8, v9, v9
	v_lshlrev_b32_e32 v9, 16, v14
	v_fmac_f32_e32 v8, v9, v9
	v_and_b32_e32 v9, 0xffff0000, v14
	v_fmac_f32_e32 v8, v9, v9
	v_lshlrev_b32_e32 v9, 16, v15
	v_fmac_f32_e32 v8, v9, v9
	v_and_b32_e32 v9, 0xffff0000, v15
	v_fmac_f32_e32 v8, v9, v9
	ds_read_b128 v[14:17], v186 offset:12384
	s_waitcnt lgkmcnt(1)
	v_lshlrev_b32_e32 v9, 16, v10
	v_fmac_f32_e32 v8, v9, v9
	v_and_b32_e32 v9, 0xffff0000, v10
	v_fmac_f32_e32 v8, v9, v9
	v_lshlrev_b32_e32 v9, 16, v11
	v_fmac_f32_e32 v8, v9, v9
	v_and_b32_e32 v9, 0xffff0000, v11
	v_fmac_f32_e32 v8, v9, v9
	v_lshlrev_b32_e32 v9, 16, v12
	v_fmac_f32_e32 v8, v9, v9
	v_and_b32_e32 v9, 0xffff0000, v12
	v_fmac_f32_e32 v8, v9, v9
	v_lshlrev_b32_e32 v9, 16, v13
	v_fmac_f32_e32 v8, v9, v9
	v_and_b32_e32 v9, 0xffff0000, v13
	v_fmac_f32_e32 v8, v9, v9
	s_waitcnt lgkmcnt(0)
	v_lshlrev_b32_e32 v9, 16, v14
	v_fmac_f32_e32 v8, v9, v9
	v_and_b32_e32 v9, 0xffff0000, v14
	v_fmac_f32_e32 v8, v9, v9
	v_lshlrev_b32_e32 v9, 16, v15
	v_fmac_f32_e32 v8, v9, v9
	v_and_b32_e32 v9, 0xffff0000, v15
	v_fmac_f32_e32 v8, v9, v9
	v_lshlrev_b32_e32 v9, 16, v16
	v_fmac_f32_e32 v8, v9, v9
	v_and_b32_e32 v9, 0xffff0000, v16
	v_fmac_f32_e32 v8, v9, v9
	v_lshlrev_b32_e32 v9, 16, v17
	v_fmac_f32_e32 v8, v9, v9
	v_and_b32_e32 v9, 0xffff0000, v17
	v_fmac_f32_e32 v8, v9, v9
	ds_bpermute_b32 v9, v159, v8
	v_cvt_f32_ubyte0_e32 v10, s1
	s_mov_b64 s[0:1], exec
	v_readlane_b32 s2, v241, 3
	v_readlane_b32 s3, v241, 4
	s_and_b64 s[2:3], s[0:1], s[2:3]
	s_mov_b64 exec, s[2:3]
	v_mov_b32_e32 v11, s71
	ds_write_b32 v11, v180
	s_or_b64 exec, exec, s[0:1]
	s_waitcnt vmcnt(0)
	v_add_f32_e32 v4, 0, v4
	v_add_f32_e32 v4, v4, v5
	v_add_f32_e32 v4, v4, v6
	v_add_f32_e32 v4, v4, v7
	v_add_f32_e32 v0, v4, v0
	v_add_f32_e32 v0, v0, v1
	v_readlane_b32 s0, v241, 37
	v_add_f32_e32 v0, v0, v2
	s_lshl_b32 s10, s4, 1
	s_add_i32 s2, s5, s0
	v_add_f32_e32 v0, v0, v3
	v_readlane_b32 s0, v240, 30
	s_waitcnt lgkmcnt(0)
	v_add_f32_e32 v1, v8, v9
	s_add_i32 s14, s10, s0
	v_mul_f32_e32 v0, v0, v1
	s_mov_b32 s0, 0xf800000
	v_cmp_gt_f32_e32 vcc, s0, v0
	v_mul_f32_e32 v1, 0x4f800000, v0
	v_exp_f32_e64 v10, -v10
	v_cndmask_b32_e32 v0, v0, v1, vcc
	v_sqrt_f32_e32 v1, v0
	s_or_b32 s12, s10, 1
	s_lshl_b32 s80, s11, 1
	s_mov_b32 s81, s21
	v_add_u32_e32 v2, -1, v1
	v_fma_f32 v3, -v2, v1, v0
	v_cmp_ge_f32_e64 s[0:1], 0, v3
	v_add_u32_e32 v3, 1, v1
	v_lshl_add_u64 v[112:113], v[134:135], 0, s[80:81]
	v_cndmask_b32_e64 v2, v1, v2, s[0:1]
	v_fma_f32 v1, -v3, v1, v0
	v_cmp_lt_f32_e64 s[0:1], 0, v1
	s_movk_i32 s3, 0x2000
	v_mul_f32_e32 v129, 0x3fb8aa3b, v10
	v_cndmask_b32_e64 v1, v2, v3, s[0:1]
	v_mul_f32_e32 v2, 0x37800000, v1
	s_lshl_b32 s0, s12, 17
	s_mov_b32 s1, s21
	v_cndmask_b32_e32 v1, v1, v2, vcc
	v_cmp_class_f32_e32 vcc, v0, v181
	v_lshl_add_u64 v[4:5], v[112:113], 0, s[0:1]
	s_lshl_b32 s0, s4, 18
	v_cndmask_b32_e32 v0, v1, v0, vcc
	v_lshl_add_u64 v[12:13], v[112:113], 0, s[0:1]
	v_fmamk_f32 v32, v0, 0x3f804189, v182
	s_nop 0
	s_nop 0
	v_add_co_u32_e32 v4, vcc, s3, v4
	v_readlane_b32 s0, v240, 21
	s_nop 0
	v_addc_co_u32_e32 v5, vcc, 0, v5, vcc
	s_nop 0
	v_add_co_u32_e32 v12, vcc, s3, v12
	v_add_u32_e32 v145, 0x100, v170
	s_nop 0
	v_addc_co_u32_e32 v13, vcc, 0, v13, vcc
	s_nop 0
	v_add_u32_e32 v33, s0, v166
	s_lshl_b32 s0, s14, 6
	v_or_b32_e32 v148, s2, v161
	s_waitcnt vmcnt(3)
	ds_write_b128 v145, v[198:201]
	s_waitcnt vmcnt(1)
	ds_write_b128 v145, v[202:205] offset:64
	ds_write_b128 v145, v[206:209] offset:33280
	s_waitcnt vmcnt(0)
	ds_write_b128 v145, v[210:213] offset:33344
	s_waitcnt lgkmcnt(0)
	s_barrier
	ds_read_b128 v[0:3], v33
	ds_read_b128 v[4:7], v33 offset:512
	ds_read_b128 v[8:11], v186
	s_waitcnt lgkmcnt(0)
	v_mfma_f32_32x32x16_bf16 v[16:31], v[0:3], v[8:11], 0
	ds_read_b128 v[34:37], v33 offset:2080
	ds_read_b128 v[38:41], v33 offset:2592
	ds_read_b128 v[42:45], v186 offset:4128
	v_mfma_f32_32x32x16_bf16 v[0:15], v[4:7], v[8:11], 0
	s_waitcnt lgkmcnt(0)
	v_mfma_f32_32x32x16_bf16 v[16:31], v[34:37], v[42:45], v[16:31]
	v_mfma_f32_32x32x16_bf16 v[0:15], v[38:41], v[42:45], v[0:15]
	ds_read_b128 v[34:37], v33 offset:4160
	ds_read_b128 v[38:41], v33 offset:4672
	ds_read_b128 v[42:45], v186 offset:8256
	s_waitcnt lgkmcnt(0)
	v_mfma_f32_32x32x16_bf16 v[16:31], v[34:37], v[42:45], v[16:31]
	v_mfma_f32_32x32x16_bf16 v[0:15], v[38:41], v[42:45], v[0:15]
	ds_read_b128 v[34:37], v33 offset:6240
	ds_read_b128 v[38:41], v33 offset:6752
	ds_read_b128 v[42:45], v186 offset:12384
	v_subrev_u32_e32 v33, s0, v171
	v_add_u32_e32 v33, v33, v148
	v_cvt_f32_i32_e32 v33, v33
	s_mov_b32 s0, 0xff61b1e6
	s_waitcnt lgkmcnt(0)
	v_mfma_f32_32x32x16_bf16 v[16:31], v[34:37], v[42:45], v[16:31]
	v_add_f32_e32 v34, 0xc2000000, v33
	v_mfma_f32_32x32x16_bf16 v[0:15], v[38:41], v[42:45], v[0:15]
	s_nop 9
	v_fma_f32 v16, -v129, |v33|, v16
	s_nop 0
	v_fma_f32 v0, -v129, |v34|, v0
	v_max_f32_e32 v0, v16, v0
	v_add_f32_e32 v16, -1.0, v33
	v_fma_f32 v16, -v129, |v16|, v17
	v_add_f32_e32 v17, 0xc2040000, v33
	v_fma_f32 v1, -v129, |v17|, v1
	v_max_f32_e32 v1, v16, v1
	v_max3_f32 v0, v0, s0, v1
	v_add_f32_e32 v1, -2.0, v33
	v_add_f32_e32 v16, 0xc2080000, v33
	v_fma_f32 v1, -v129, |v1|, v18
	v_fma_f32 v2, -v129, |v16|, v2
	v_max_f32_e32 v1, v1, v2
	v_add_f32_e32 v2, 0xc0400000, v33
	v_add_f32_e32 v16, 0xc20c0000, v33
	v_fma_f32 v2, -v129, |v2|, v19
	v_fma_f32 v3, -v129, |v16|, v3
	v_max_f32_e32 v2, v2, v3
	v_max3_f32 v0, v0, v1, v2
	v_add_f32_e32 v1, -4.0, v33
	v_add_f32_e32 v2, 0xc2100000, v33
	v_fma_f32 v1, -v129, |v1|, v20
	v_fma_f32 v2, -v129, |v2|, v4
	v_max_f32_e32 v1, v1, v2
	v_add_f32_e32 v2, 0xc0a00000, v33
	v_add_f32_e32 v3, 0xc2140000, v33
	v_fma_f32 v2, -v129, |v2|, v21
	v_fma_f32 v3, -v129, |v3|, v5
	v_max_f32_e32 v2, v2, v3
	v_max3_f32 v0, v0, v1, v2
	v_add_f32_e32 v1, 0xc0c00000, v33
	v_add_f32_e32 v2, 0xc2180000, v33
	v_fma_f32 v1, -v129, |v1|, v22
	v_fma_f32 v2, -v129, |v2|, v6
	v_max_f32_e32 v1, v1, v2
	v_add_f32_e32 v2, 0xc0e00000, v33
	v_add_f32_e32 v3, 0xc21c0000, v33
	v_fma_f32 v2, -v129, |v2|, v23
	v_fma_f32 v3, -v129, |v3|, v7
	v_max_f32_e32 v2, v2, v3
	v_max3_f32 v0, v0, v1, v2
	v_add_f32_e32 v1, 0xc1800000, v33
	v_add_f32_e32 v2, 0xc2400000, v33
	v_fma_f32 v1, -v129, |v1|, v24
	v_fma_f32 v2, -v129, |v2|, v8
	v_max_f32_e32 v1, v1, v2
	v_add_f32_e32 v2, 0xc1880000, v33
	v_add_f32_e32 v3, 0xc2440000, v33
	v_fma_f32 v2, -v129, |v2|, v25
	v_fma_f32 v3, -v129, |v3|, v9
	v_max_f32_e32 v2, v2, v3
	v_max3_f32 v0, v0, v1, v2
	v_add_f32_e32 v1, 0xc1900000, v33
	v_add_f32_e32 v2, 0xc2480000, v33
	v_fma_f32 v1, -v129, |v1|, v26
	v_fma_f32 v2, -v129, |v2|, v10
	v_max_f32_e32 v1, v1, v2
	v_add_f32_e32 v2, 0xc1980000, v33
	v_add_f32_e32 v3, 0xc24c0000, v33
	v_fma_f32 v2, -v129, |v2|, v27
	v_fma_f32 v3, -v129, |v3|, v11
	v_max_f32_e32 v2, v2, v3
	v_max3_f32 v0, v0, v1, v2
	v_add_f32_e32 v1, 0xc1a00000, v33
	v_add_f32_e32 v2, 0xc2500000, v33
	v_fma_f32 v1, -v129, |v1|, v28
	v_fma_f32 v2, -v129, |v2|, v12
	v_max_f32_e32 v1, v1, v2
	v_add_f32_e32 v2, 0xc1a80000, v33
	v_add_f32_e32 v3, 0xc2540000, v33
	v_fma_f32 v2, -v129, |v2|, v29
	v_fma_f32 v3, -v129, |v3|, v13
	v_max_f32_e32 v2, v2, v3
	v_max3_f32 v0, v0, v1, v2
	v_add_f32_e32 v1, 0xc1b00000, v33
	v_add_f32_e32 v2, 0xc2580000, v33
	v_fma_f32 v1, -v129, |v1|, v30
	v_fma_f32 v2, -v129, |v2|, v14
	v_max_f32_e32 v1, v1, v2
	v_add_f32_e32 v2, 0xc1b80000, v33
	v_add_f32_e32 v3, 0xc25c0000, v33
	v_fma_f32 v2, -v129, |v2|, v31
	v_fma_f32 v3, -v129, |v3|, v15
	v_max_f32_e32 v2, v2, v3
	v_max3_f32 v0, v0, v1, v2
	ds_bpermute_b32 v1, v159, v0
	s_waitcnt lgkmcnt(0)
	v_max_f32_e32 v1, v1, v1
	v_max_f32_e32 v149, v0, v1
	v_sub_f32_e32 v0, v32, v149
	ds_bpermute_b32 v1, v154, v0
	s_waitcnt lgkmcnt(0)
	v_max_f32_e32 v1, v1, v1
	v_max_f32_e32 v0, v0, v1
	ds_bpermute_b32 v1, v155, v0
	s_waitcnt lgkmcnt(0)
	v_max_f32_e32 v1, v1, v1
	v_max_f32_e32 v0, v0, v1
	ds_bpermute_b32 v1, v156, v0
	s_waitcnt lgkmcnt(0)
	v_max_f32_e32 v1, v1, v1
	v_max_f32_e32 v0, v0, v1
	ds_bpermute_b32 v1, v157, v0
	s_waitcnt lgkmcnt(0)
	v_max_f32_e32 v1, v1, v1
	v_max_f32_e32 v0, v0, v1
	ds_bpermute_b32 v1, v158, v0
	s_mov_b64 s[0:1], exec
	v_readlane_b32 s16, v240, 32
	v_readlane_b32 s17, v240, 33
	s_and_b64 s[16:17], s[0:1], s[16:17]
	s_mov_b64 exec, s[16:17]
	s_cbranch_execz .LBB0_575
	s_waitcnt lgkmcnt(0)
	v_max_f32_e32 v1, v1, v1
	v_max_f32_e32 v0, v0, v0
	v_max_f32_e32 v0, v0, v1
	s_sub_i32 s2, s2, 63
	v_add_f32_e32 v0, 0x43080000, v0
	v_cvt_f32_i32_e32 v1, s2
	v_div_scale_f32 v2, s[2:3], v129, v129, v0
	v_rcp_f32_e32 v3, v2
	s_brev_b32 s13, -2
	s_mov_b64 s[2:3], exec
	v_fma_f32 v4, -v2, v3, 1.0
	v_fmac_f32_e32 v3, v4, v3
	v_div_scale_f32 v4, vcc, v0, v129, v0
	v_mul_f32_e32 v5, v4, v3
	v_fma_f32 v6, -v2, v5, v4
	v_fmac_f32_e32 v5, v6, v3
	v_fma_f32 v2, -v2, v5, v4
	v_div_fmas_f32 v2, v2, v3, v5
	v_div_fixup_f32 v0, v2, v129, v0
	v_sub_f32_e32 v0, v1, v0
	v_mul_f32_e32 v0, 0x3c800000, v0
	v_ceil_f32_e32 v1, v0
	v_cvt_i32_f32_e32 v1, v1
	v_cmp_lt_f32_e32 vcc, 0, v0
	s_nop 1
	v_cndmask_b32_e32 v0, 0, v1, vcc

.LBB0_580:
	s_mov_b32 s98, 0
	v_cndmask_b32_e64 v0, 0, 1, s[12:13]
	v_cmp_ne_u32_e64 s[0:1], 1, v0
	s_andn2_b64 vcc, exec, s[12:13]
	v_mov_b32_e32 v187, v64
	s_cbranch_vccnz .LBB0_582
	global_load_dwordx4 v[96:99], v[116:117], off
	global_load_dwordx4 v[100:103], v[118:119], off
	global_load_dwordx4 v[104:107], v[120:121], off
	global_load_dwordx4 v[108:111], v[124:125], off
	v_add_u32_e32 v0, 0x100, v172
	s_waitcnt vmcnt(3)
	ds_write_b128 v145, v[96:99]
	s_waitcnt vmcnt(2)
	ds_write_b128 v145, v[100:103] offset:64
	s_waitcnt vmcnt(1)
	ds_write_b128 v0, v[104:107] offset:16640
	s_waitcnt vmcnt(0)
	ds_write_b128 v0, v[108:111] offset:16768

.LBB0_589:
	s_bitcmp1_b32 s70, 0
	v_cvt_f32_i32_e32 v130, v190
	s_cselect_b32 s1, 0x8200, 0
	s_addk_i32 s1, 0x100
	s_cmp_eq_u32 s4, s70
	s_cbranch_scc1 .Latt_diag
	s_cmp_eq_u32 s98, 0
	s_cbranch_scc1 .Lfl_fast
	s_mov_b32 s98, 0
	v_mfma_f32_32x32x16_bf16 v[48:63], v[206:209], v[76:79], v[48:63]
	v_mfma_f32_32x32x16_bf16 v[32:47], v[210:213], v[76:79], v[32:47]
	v_mfma_f32_32x32x16_bf16 v[16:31], v[214:217], v[76:79], v[16:31]
	v_mfma_f32_32x32x16_bf16 v[0:15], v[218:221], v[76:79], v[0:15]
.Lfl_fast:
	v_add_u32_e32 v127, s1, v166
	ds_read_b128 v[198:201], v127
	ds_read_b128 v[222:225], v186
	ds_read_b128 v[202:205], v127 offset:2080
	ds_read_b128 v[226:229], v186 offset:4128
	ds_read_b128 v[206:209], v127 offset:4160
	ds_read_b128 v[230:233], v186 offset:8256
	ds_read_b128 v[210:213], v127 offset:6240
	ds_read_b128 v[234:237], v186 offset:12384
	ds_read_b128 v[214:217], v127 offset:512
	ds_read_b128 v[218:221], v127 offset:2592
	v_fma_f32 v192, -v129, v130, -v188
	v_mov_b32_e32 v80, v129
	v_add3_u32 v191, s1, v167, v168
	v_fma_f32 v64, 0, v80, v192
	v_add_f32_e32 v65, v80, v192
	v_pk_fma_f32 v[66:67], v[80:81], s[84:85], v[192:193] op_sel_hi:[0,1,0]
	v_pk_fma_f32 v[68:69], v[80:81], s[86:87], v[192:193] op_sel_hi:[0,1,0]
	v_pk_fma_f32 v[70:71], v[80:81], s[88:89], v[192:193] op_sel_hi:[0,1,0]
	v_pk_fma_f32 v[72:73], v[80:81], s[90:91], v[192:193] op_sel_hi:[0,1,0]
	v_pk_fma_f32 v[74:75], v[80:81], s[92:93], v[192:193] op_sel_hi:[0,1,0]
	v_pk_fma_f32 v[76:77], v[80:81], s[94:95], v[192:193] op_sel_hi:[0,1,0]
	v_pk_fma_f32 v[78:79], v[80:81], s[96:97], v[192:193] op_sel_hi:[0,1,0]
	v_pk_fma_f32 v[94:95], v[80:81], s[22:23], v[192:193] op_sel_hi:[0,1,0]
	v_pk_fma_f32 v[92:93], v[80:81], s[74:75], v[192:193] op_sel_hi:[0,1,0]
	v_pk_fma_f32 v[90:91], v[80:81], s[76:77], v[192:193] op_sel_hi:[0,1,0]
	v_pk_fma_f32 v[88:89], v[80:81], s[24:25], v[192:193] op_sel_hi:[0,1,0]
	v_pk_fma_f32 v[86:87], v[80:81], s[26:27], v[192:193] op_sel_hi:[0,1,0]
	v_pk_fma_f32 v[84:85], v[80:81], s[72:73], v[192:193] op_sel_hi:[0,1,0]
	v_pk_fma_f32 v[82:83], v[80:81], s[18:19], v[192:193] op_sel_hi:[0,1,0]
	v_pk_fma_f32 v[80:81], v[80:81], s[34:35], v[192:193] op_sel_hi:[0,1,0]
	ds_read_b128 v[192:195], v127 offset:4672
	s_waitcnt lgkmcnt(9)
	v_mfma_f32_32x32x16_bf16 v[64:79], v[198:201], v[222:225], v[64:79]
	ds_read_b128 v[198:201], v127 offset:6752
	s_waitcnt lgkmcnt(8)
	v_mfma_f32_32x32x16_bf16 v[64:79], v[202:205], v[226:229], v[64:79]
	s_waitcnt lgkmcnt(6)
	v_mfma_f32_32x32x16_bf16 v[64:79], v[206:209], v[230:233], v[64:79]
	s_waitcnt lgkmcnt(4)
	v_mfma_f32_32x32x16_bf16 v[64:79], v[210:213], v[234:237], v[64:79]
	ds_read_b128 v[202:205], v191 offset:16640
	ds_read_b128 v[206:209], v191 offset:17152
	ds_read_b128 v[210:213], v191 offset:17664
	s_waitcnt lgkmcnt(6)
	v_mfma_f32_32x32x16_bf16 v[80:95], v[214:217], v[222:225], v[80:95]
	s_waitcnt lgkmcnt(5)
	v_mfma_f32_32x32x16_bf16 v[80:95], v[218:221], v[226:229], v[80:95]
	s_waitcnt lgkmcnt(4)
	v_mfma_f32_32x32x16_bf16 v[80:95], v[192:195], v[230:233], v[80:95]
	s_waitcnt lgkmcnt(3)
	v_mfma_f32_32x32x16_bf16 v[80:95], v[198:201], v[234:237], v[80:95]
	ds_read_b128 v[214:217], v191 offset:18176
	ds_read_b128 v[218:221], v191 offset:20768
	ds_read_b128 v[192:195], v191 offset:21280
	ds_read_b128 v[198:201], v191 offset:21792
	ds_read_b128 v[222:225], v191 offset:22304
	ds_read_b128 v[226:229], v191 offset:24896
	ds_read_b128 v[230:233], v191 offset:25408
	ds_read_b128 v[234:237], v191 offset:25920
	v_exp_f32_e32 v64, v64
	v_exp_f32_e32 v65, v65
	v_exp_f32_e32 v66, v66
	v_exp_f32_e32 v67, v67
	v_exp_f32_e32 v68, v68
	v_exp_f32_e32 v69, v69
	v_exp_f32_e32 v70, v70
	v_exp_f32_e32 v71, v71
	v_add_f32_e32 v130, v64, v65
	v_add_f32_e32 v130, v130, v66
	v_add_f32_e32 v130, v130, v67
	v_add_f32_e32 v130, v130, v68
	v_add_f32_e32 v130, v130, v69
	v_add_f32_e32 v130, v130, v70
	v_add_f32_e32 v130, v130, v71
	v_cvt_pk_bf16_f32 v64, v64, v65
	v_cvt_pk_bf16_f32 v65, v66, v67
	v_cvt_pk_bf16_f32 v66, v68, v69
	v_cvt_pk_bf16_f32 v67, v70, v71
	s_waitcnt lgkmcnt(10)
	v_exp_f32_e32 v72, v72
	v_mfma_f32_32x32x16_bf16 v[48:63], v[202:205], v[64:67], v[48:63]
	v_exp_f32_e32 v73, v73
	v_exp_f32_e32 v74, v74
	v_add_f32_e32 v130, v130, v72
	v_add_f32_e32 v130, v130, v73
	s_waitcnt lgkmcnt(9)
	v_mfma_f32_32x32x16_bf16 v[32:47], v[206:209], v[64:67], v[32:47]
	v_exp_f32_e32 v75, v75
	v_exp_f32_e32 v76, v76
	v_cvt_pk_bf16_f32 v68, v72, v73
	v_add_f32_e32 v130, v130, v74
	s_waitcnt lgkmcnt(8)
	v_mfma_f32_32x32x16_bf16 v[16:31], v[210:213], v[64:67], v[16:31]
	v_exp_f32_e32 v77, v77
	v_exp_f32_e32 v78, v78
	v_cvt_pk_bf16_f32 v69, v74, v75
	v_add_f32_e32 v130, v130, v75
	v_add_f32_e32 v130, v130, v76
	s_waitcnt lgkmcnt(7)
	v_mfma_f32_32x32x16_bf16 v[0:15], v[214:217], v[64:67], v[0:15]
	ds_read_b128 v[202:205], v191 offset:26432
	ds_read_b128 v[206:209], v191 offset:29024
	ds_read_b128 v[210:213], v191 offset:29536
	ds_read_b128 v[214:217], v191 offset:30048
	v_exp_f32_e32 v79, v79
	v_cvt_pk_bf16_f32 v70, v76, v77
	v_add_f32_e32 v130, v130, v77
	v_add_f32_e32 v130, v130, v78
	v_add_f32_e32 v130, v130, v79
	v_cvt_pk_bf16_f32 v71, v78, v79
	s_waitcnt lgkmcnt(10)
	v_exp_f32_e32 v80, v80
	v_mfma_f32_32x32x16_bf16 v[48:63], v[218:221], v[68:71], v[48:63]
	v_exp_f32_e32 v81, v81
	v_exp_f32_e32 v82, v82
	v_add_f32_e32 v130, v130, v80
	v_add_f32_e32 v130, v130, v81
	s_waitcnt lgkmcnt(9)
	v_mfma_f32_32x32x16_bf16 v[32:47], v[192:195], v[68:71], v[32:47]
	v_exp_f32_e32 v83, v83
	v_exp_f32_e32 v84, v84
	v_cvt_pk_bf16_f32 v72, v80, v81
	v_add_f32_e32 v130, v130, v82
	s_waitcnt lgkmcnt(8)
	v_mfma_f32_32x32x16_bf16 v[16:31], v[198:201], v[68:71], v[16:31]
	v_exp_f32_e32 v85, v85
	v_exp_f32_e32 v86, v86
	v_cvt_pk_bf16_f32 v73, v82, v83
	v_add_f32_e32 v130, v130, v83
	v_add_f32_e32 v130, v130, v84
	s_waitcnt lgkmcnt(7)
	v_mfma_f32_32x32x16_bf16 v[0:15], v[222:225], v[68:71], v[0:15]
	ds_read_b128 v[218:221], v191 offset:30560
	v_exp_f32_e32 v87, v87
	v_cvt_pk_bf16_f32 v74, v84, v85
	v_add_f32_e32 v130, v130, v85
	v_add_f32_e32 v130, v130, v86
	v_add_f32_e32 v130, v130, v87
	v_cvt_pk_bf16_f32 v75, v86, v87
	s_waitcnt lgkmcnt(7)
	v_exp_f32_e32 v88, v88
	v_mfma_f32_32x32x16_bf16 v[48:63], v[226:229], v[72:75], v[48:63]
	v_exp_f32_e32 v89, v89
	v_exp_f32_e32 v90, v90
	v_add_f32_e32 v130, v130, v88
	v_add_f32_e32 v130, v130, v89
	s_waitcnt lgkmcnt(6)
	v_mfma_f32_32x32x16_bf16 v[32:47], v[230:233], v[72:75], v[32:47]
	v_exp_f32_e32 v91, v91
	v_exp_f32_e32 v92, v92
	v_cvt_pk_bf16_f32 v76, v88, v89
	v_add_f32_e32 v130, v130, v90
	s_waitcnt lgkmcnt(5)
	v_mfma_f32_32x32x16_bf16 v[16:31], v[234:237], v[72:75], v[16:31]
	v_exp_f32_e32 v93, v93
	v_exp_f32_e32 v94, v94
	v_cvt_pk_bf16_f32 v77, v90, v91
	v_add_f32_e32 v130, v130, v91
	v_add_f32_e32 v130, v130, v92
	s_waitcnt lgkmcnt(4)
	v_mfma_f32_32x32x16_bf16 v[0:15], v[202:205], v[72:75], v[0:15]
	v_exp_f32_e32 v95, v95
	v_cvt_pk_bf16_f32 v78, v92, v93
	v_add_f32_e32 v130, v130, v93
	v_add_f32_e32 v130, v130, v94
	v_add_f32_e32 v130, v130, v95
	v_cvt_pk_bf16_f32 v79, v94, v95
	s_waitcnt lgkmcnt(0)
	s_mov_b32 s98, 1
	v_add_f32_e32 v150, v150, v130
	s_branch .Latt_join
.Latt_diag:
	s_cmp_eq_u32 s98, 0
	s_cbranch_scc1 .Lfl_diag
	s_mov_b32 s98, 0
	v_mfma_f32_32x32x16_bf16 v[48:63], v[206:209], v[76:79], v[48:63]
	v_mfma_f32_32x32x16_bf16 v[32:47], v[210:213], v[76:79], v[32:47]
	v_mfma_f32_32x32x16_bf16 v[16:31], v[214:217], v[76:79], v[16:31]
	v_mfma_f32_32x32x16_bf16 v[0:15], v[218:221], v[76:79], v[0:15]
.Lfl_diag:
	s_mov_b64 vcc, -1
	v_fma_f32 v64, -v129, v130, -v188
	v_cndmask_b32_e64 v80, v129, 0, vcc
	v_cndmask_b32_e32 v192, v64, v189, vcc
	v_add_u32_e32 v127, s1, v166
	v_fma_f32 v64, 0, v80, v192
	v_add_f32_e32 v65, v80, v192
	v_pk_fma_f32 v[66:67], v[80:81], s[84:85], v[192:193] op_sel_hi:[0,1,0]
	v_pk_fma_f32 v[68:69], v[80:81], s[86:87], v[192:193] op_sel_hi:[0,1,0]
	v_pk_fma_f32 v[70:71], v[80:81], s[88:89], v[192:193] op_sel_hi:[0,1,0]
	v_pk_fma_f32 v[72:73], v[80:81], s[90:91], v[192:193] op_sel_hi:[0,1,0]
	v_pk_fma_f32 v[74:75], v[80:81], s[92:93], v[192:193] op_sel_hi:[0,1,0]
	v_pk_fma_f32 v[76:77], v[80:81], s[94:95], v[192:193] op_sel_hi:[0,1,0]
	v_pk_fma_f32 v[78:79], v[80:81], s[96:97], v[192:193] op_sel_hi:[0,1,0]
	v_pk_fma_f32 v[94:95], v[80:81], s[22:23], v[192:193] op_sel_hi:[0,1,0]
	v_pk_fma_f32 v[92:93], v[80:81], s[74:75], v[192:193] op_sel_hi:[0,1,0]
	v_pk_fma_f32 v[90:91], v[80:81], s[76:77], v[192:193] op_sel_hi:[0,1,0]
	v_pk_fma_f32 v[88:89], v[80:81], s[24:25], v[192:193] op_sel_hi:[0,1,0]
	v_pk_fma_f32 v[86:87], v[80:81], s[26:27], v[192:193] op_sel_hi:[0,1,0]
	v_pk_fma_f32 v[84:85], v[80:81], s[72:73], v[192:193] op_sel_hi:[0,1,0]
	v_pk_fma_f32 v[82:83], v[80:81], s[18:19], v[192:193] op_sel_hi:[0,1,0]
	v_pk_fma_f32 v[80:81], v[80:81], s[34:35], v[192:193] op_sel_hi:[0,1,0]
	ds_read_b128 v[192:195], v127
	ds_read_b128 v[198:201], v127 offset:512
	ds_read_b128 v[202:205], v186
	s_waitcnt lgkmcnt(0)
	v_mfma_f32_32x32x16_bf16 v[64:79], v[192:195], v[202:205], v[64:79]
	s_cmp_lg_u32 s4, s70
	v_mfma_f32_32x32x16_bf16 v[80:95], v[198:201], v[202:205], v[80:95]
	ds_read_b128 v[192:195], v127 offset:2080
	ds_read_b128 v[198:201], v127 offset:2592
	ds_read_b128 v[202:205], v186 offset:4128
	s_waitcnt lgkmcnt(0)
	v_mfma_f32_32x32x16_bf16 v[64:79], v[192:195], v[202:205], v[64:79]
	v_mfma_f32_32x32x16_bf16 v[80:95], v[198:201], v[202:205], v[80:95]
	ds_read_b128 v[192:195], v127 offset:4160
	ds_read_b128 v[198:201], v127 offset:4672
	ds_read_b128 v[202:205], v186 offset:8256
	s_waitcnt lgkmcnt(0)
	v_mfma_f32_32x32x16_bf16 v[64:79], v[192:195], v[202:205], v[64:79]
	v_mfma_f32_32x32x16_bf16 v[80:95], v[198:201], v[202:205], v[80:95]
	ds_read_b128 v[192:195], v127 offset:6240
	ds_read_b128 v[198:201], v127 offset:6752
	ds_read_b128 v[202:205], v186 offset:12384
	s_waitcnt lgkmcnt(0)
	v_mfma_f32_32x32x16_bf16 v[64:79], v[192:195], v[202:205], v[64:79]
	v_mfma_f32_32x32x16_bf16 v[80:95], v[198:201], v[202:205], v[80:95]
	s_cbranch_scc1 .LBB0_591
	v_add_f32_e32 v127, -1.0, v130
	v_pk_add_f32 v[192:193], v[130:131], s[42:43] op_sel_hi:[0,1]
	v_pk_add_f32 v[194:195], v[130:131], s[46:47] op_sel_hi:[0,1]
	v_pk_add_f32 v[198:199], v[130:131], s[50:51] op_sel_hi:[0,1]
	v_pk_add_f32 v[200:201], v[130:131], s[54:55] op_sel_hi:[0,1]
	v_pk_add_f32 v[202:203], v[130:131], s[58:59] op_sel_hi:[0,1]
	v_pk_add_f32 v[204:205], v[130:131], s[62:63] op_sel_hi:[0,1]
	v_pk_add_f32 v[206:207], v[130:131], s[66:67] op_sel_hi:[0,1]
	v_and_b32_e32 v193, 0x7fffffff, v193
	v_and_b32_e32 v192, 0x7fffffff, v192
	v_and_b32_e32 v195, 0x7fffffff, v195
	v_and_b32_e32 v194, 0x7fffffff, v194
	v_and_b32_e32 v199, 0x7fffffff, v199
	v_and_b32_e32 v198, 0x7fffffff, v198
	v_and_b32_e32 v201, 0x7fffffff, v201
	v_and_b32_e32 v200, 0x7fffffff, v200
	v_and_b32_e32 v203, 0x7fffffff, v203
	v_and_b32_e32 v202, 0x7fffffff, v202
	v_and_b32_e32 v205, 0x7fffffff, v205
	v_and_b32_e32 v204, 0x7fffffff, v204
	v_and_b32_e32 v207, 0x7fffffff, v207
	v_and_b32_e32 v206, 0x7fffffff, v206
	v_and_b32_e32 v208, 0x7fffffff, v130
	v_and_b32_e32 v209, 0x7fffffff, v127
	v_mov_b32_e32 v127, v126
	v_pk_fma_f32 v[78:79], v[126:127], v[206:207], v[78:79]
	v_pk_fma_f32 v[76:77], v[126:127], v[204:205], v[76:77]
	v_pk_fma_f32 v[74:75], v[126:127], v[202:203], v[74:75]
	v_pk_fma_f32 v[72:73], v[126:127], v[200:201], v[72:73]
	v_pk_fma_f32 v[70:71], v[126:127], v[198:199], v[70:71]
	v_pk_fma_f32 v[68:69], v[126:127], v[194:195], v[68:69]
	v_pk_fma_f32 v[66:67], v[126:127], v[192:193], v[66:67]
	v_pk_fma_f32 v[64:65], v[152:153], v[208:209], v[64:65]
	v_pk_add_f32 v[192:193], v[130:131], s[82:83] op_sel_hi:[0,1]
	v_pk_add_f32 v[194:195], v[130:131], s[64:65] op_sel_hi:[0,1]
	v_pk_add_f32 v[198:199], v[130:131], s[60:61] op_sel_hi:[0,1]
	v_pk_add_f32 v[200:201], v[130:131], s[56:57] op_sel_hi:[0,1]
	v_pk_add_f32 v[202:203], v[130:131], s[52:53] op_sel_hi:[0,1]
	v_pk_add_f32 v[204:205], v[130:131], s[48:49] op_sel_hi:[0,1]
	v_pk_add_f32 v[206:207], v[130:131], s[44:45] op_sel_hi:[0,1]
	v_pk_add_f32 v[208:209], v[130:131], s[40:41] op_sel_hi:[0,1]
	v_and_b32_e32 v209, 0x7fffffff, v209
	v_and_b32_e32 v208, 0x7fffffff, v208
	v_and_b32_e32 v207, 0x7fffffff, v207
	v_and_b32_e32 v206, 0x7fffffff, v206
	v_and_b32_e32 v205, 0x7fffffff, v205
	v_and_b32_e32 v204, 0x7fffffff, v204
	v_and_b32_e32 v203, 0x7fffffff, v203
	v_and_b32_e32 v202, 0x7fffffff, v202
	v_and_b32_e32 v201, 0x7fffffff, v201
	v_and_b32_e32 v200, 0x7fffffff, v200
	v_and_b32_e32 v199, 0x7fffffff, v199
	v_and_b32_e32 v198, 0x7fffffff, v198
	v_and_b32_e32 v195, 0x7fffffff, v195
	v_and_b32_e32 v194, 0x7fffffff, v194
	v_and_b32_e32 v193, 0x7fffffff, v193
	v_and_b32_e32 v192, 0x7fffffff, v192
	v_pk_fma_f32 v[94:95], v[126:127], v[192:193], v[94:95]
	v_pk_fma_f32 v[92:93], v[126:127], v[194:195], v[92:93]
	v_pk_fma_f32 v[90:91], v[126:127], v[198:199], v[90:91]
	v_pk_fma_f32 v[88:89], v[126:127], v[200:201], v[88:89]
	v_pk_fma_f32 v[86:87], v[126:127], v[202:203], v[86:87]
	v_pk_fma_f32 v[84:85], v[126:127], v[204:205], v[84:85]
	v_pk_fma_f32 v[82:83], v[126:127], v[206:207], v[82:83]
	v_pk_fma_f32 v[80:81], v[152:153], v[208:209], v[80:81]

.LBB0_594:
	s_cmp_eq_u32 s98, 0
	s_cbranch_scc1 .Lfl_exit
	s_mov_b32 s98, 0
	v_mfma_f32_32x32x16_bf16 v[48:63], v[206:209], v[76:79], v[48:63]
	v_mfma_f32_32x32x16_bf16 v[32:47], v[210:213], v[76:79], v[32:47]
	v_mfma_f32_32x32x16_bf16 v[16:31], v[214:217], v[76:79], v[16:31]
	v_mfma_f32_32x32x16_bf16 v[0:15], v[218:221], v[76:79], v[0:15]
	s_nop 11
